# attention bias tiles: the 8 bias-table LDS reads of a row block issued together with one wait (were 7 serialized round trips)
# baseline (speedup 1.0000x reference)
; #define LAS __attribute__((address_space(3)))
; __device__ __forceinline__ void unit(unsigned char* ws, LAS unsigned char* lds, int b, int h, int mp, int qb, const int tid_in) {
;     ...
;             if (nearb) {
;                 const LAS float* tb = TB + (256 + qw0 + 16 * g + fr - (k0 + 4 * fq));
; #pragma unroll
;                 for (int jt = 0; jt < 4; ++jt)
; #pragma unroll
;                     for (int jj = 0; jj < 4; ++jj) { const float bv = tb[-(16 * jt + jj)]; float x = s[g][jt][jj];
;                         asm("v_add_f32_e32 %0, %1, %2" : "=v"(x) : "v"(x), "v"(bv));
;                         s[g][jt][jj] = x; }
;             }
.LBB0_185:
	s_andn2_b64 vcc, exec, s[60:61]
	s_cbranch_vccnz .LBB0_187
	ds_read2_b32 v[206:207], v176 offset0:50 offset1:51
	ds_read2_b32 v[208:209], v176 offset0:48 offset1:49
	ds_read2_b32 v[210:211], v176 offset0:34 offset1:35
	ds_read2_b32 v[212:213], v176 offset0:32 offset1:33
	ds_read2_b32 v[214:215], v176 offset0:18 offset1:19
	ds_read2_b32 v[216:217], v176 offset0:16 offset1:17
	ds_read2_b32 v[218:219], v176 offset1:1
	ds_read2_b32 v[220:221], v176 offset0:2 offset1:3
	s_waitcnt lgkmcnt(0)
	v_add_f32_e32 v126, v126, v207
	v_add_f32_e32 v127, v127, v206
	v_add_f32_e32 v128, v128, v209
	v_add_f32_e32 v129, v129, v208
	v_add_f32_e32 v130, v130, v211
	v_add_f32_e32 v131, v131, v210
	v_add_f32_e32 v132, v132, v213
	v_add_f32_e32 v133, v133, v212
	v_add_f32_e32 v138, v138, v215
	v_add_f32_e32 v139, v139, v214
	v_add_f32_e32 v140, v140, v217
	v_add_f32_e32 v141, v141, v216
	v_add_f32_e32 v142, v142, v221
	v_add_f32_e32 v143, v143, v220
	v_add_f32_e32 v144, v144, v219
	v_add_f32_e32 v145, v145, v218

; #define LAS __attribute__((address_space(3)))
; __device__ __forceinline__ void unit(unsigned char* ws, LAS unsigned char* lds, int b, int h, int mp, int qb, const int tid_in) {
;     ...
;             if (nearb) {
;                 const LAS float* tb = TB + (256 + qw0 + 16 * g + fr - (k0 + 4 * fq));
; #pragma unroll
;                 for (int jt = 0; jt < 4; ++jt)
; #pragma unroll
;                     for (int jj = 0; jj < 4; ++jj) { const float bv = tb[-(16 * jt + jj)]; float x = s[g][jt][jj];
;                         asm("v_add_f32_e32 %0, %1, %2" : "=v"(x) : "v"(x), "v"(bv));
;                         s[g][jt][jj] = x; }
;             }
.LBB0_191:
	s_andn2_b64 vcc, exec, s[22:23]
	s_cbranch_vccnz .LBB0_193
	ds_read2_b32 v[206:207], v176 offset0:66 offset1:67
	ds_read2_b32 v[208:209], v176 offset0:64 offset1:65
	ds_read2_b32 v[210:211], v176 offset0:50 offset1:51
	ds_read2_b32 v[212:213], v176 offset0:48 offset1:49
	ds_read2_b32 v[214:215], v176 offset0:34 offset1:35
	ds_read2_b32 v[216:217], v176 offset0:32 offset1:33
	ds_read2_b32 v[218:219], v176 offset0:16 offset1:17
	ds_read2_b32 v[220:221], v176 offset0:18 offset1:19
	s_waitcnt lgkmcnt(0)
	v_add_f32_e32 v114, v114, v207
	v_add_f32_e32 v115, v115, v206
	v_add_f32_e32 v116, v116, v209
	v_add_f32_e32 v117, v117, v208
	v_add_f32_e32 v118, v118, v211
	v_add_f32_e32 v119, v119, v210
	v_add_f32_e32 v120, v120, v213
	v_add_f32_e32 v121, v121, v212
	v_add_f32_e32 v122, v122, v215
	v_add_f32_e32 v123, v123, v214
	v_add_f32_e32 v124, v124, v217
	v_add_f32_e32 v125, v125, v216
	v_add_f32_e32 v134, v134, v221
	v_add_f32_e32 v135, v135, v220
	v_add_f32_e32 v136, v136, v219
	v_add_f32_e32 v137, v137, v218
